# P0b bias vectors: new row-per-lane dot-product kernel (same f32 FMA math, no DPP wave reductions)
# speedup vs baseline: 1.0200x; 1.0052x over previous
.LBB0_171:
	s_barrier
	s_and_saveexec_b64 s[52:53], s[4:5]
	s_cbranch_execz .LBB0_174
	s_lshl_b32 s0, s50, 2
	s_add_u32 s60, s60, s0
	s_addc_u32 s61, s61, 0
	s_mul_i32 s0, s62, 17
	s_mov_b64 s[50:51], 0
	v_mov_b64_e32 v[6:7], s[60:61]
	v_and_b32_e32 v8, 0xff, v181
	v_lshrrev_b32_e32 v207, 6, v8
	v_add_u32_e32 v8, v8, v207
	v_lshlrev_b32_e32 v8, 4, v8
	v_lshrrev_b32_e32 v207, 8, v181
	v_mul_u32_u24_e32 v207, 0x1040, v207
	v_add_u32_e32 v8, v8, v207
	v_mov_b32_e32 v9, v1
.LBB0_173:
	v_ashrrev_i32_e32 v4, 10, v9
	v_and_b32_e32 v18, 0x3fc, v9
	v_add_u32_e32 v19, s0, v4
	v_lshlrev_b32_e32 v4, 2, v18
	v_mad_i64_i32 v[18:19], s[60:61], v19, s57, v[6:7]
	v_lshl_add_u64 v[18:19], v[18:19], 0, v[4:5]
	global_load_dwordx4 v[18:21], v[18:19], off
	v_add_u32_e32 v4, 0x800, v9
	v_cmp_lt_i32_e32 vcc, s58, v9
	s_or_b64 s[50:51], vcc, s[50:51]
	v_mov_b32_e32 v9, v4
	s_waitcnt vmcnt(0)
	ds_write_b128 v8, v[18:21]
	v_add_u32_e32 v8, 0x2080, v8
	s_andn2_b64 exec, exec, s[50:51]
	s_cbranch_execnz .LBB0_173

.LBB0_176:
	v_and_b32_e32 v128, 15, v0
	v_lshrrev_b32_e32 v129, 4, v0
	v_lshlrev_b32_e32 v208, 11, v128
	v_lshl_add_u32 v208, v129, 9, v208
	v_lshlrev_b32_e32 v207, 3, v0
	v_sub_u32_e32 v208, v208, v207
	v_mov_b32_e32 v209, 0
	v_lshl_add_u64 v[132:133], v[8:9], 0, v[208:209]
	global_load_dwordx4 v[134:137], v[132:133], off
	v_mul_u32_u24_e32 v129, 0x410, v129
	v_add_u32_e32 v130, 0x8200, v129
	v_lshlrev_b32_e32 v128, 2, v128
	v_readlane_b32 s64, v4, 1
	s_mov_b32 s63, 0
	s_mov_b64 s[70:71], 16
	v_mov_b32_e32 v190, 0
	v_mov_b32_e32 v191, 0
	v_mov_b32_e32 v192, 0
	v_mov_b32_e32 v193, 0
	v_mov_b32_e32 v194, 0
	v_mov_b32_e32 v195, 0
	v_mov_b32_e32 v196, 0
	v_mov_b32_e32 v197, 0
	v_mov_b32_e32 v198, 0
	v_mov_b32_e32 v199, 0
	v_mov_b32_e32 v200, 0
	v_mov_b32_e32 v201, 0
	v_mov_b32_e32 v202, 0
	v_mov_b32_e32 v203, 0
	v_mov_b32_e32 v204, 0
	v_mov_b32_e32 v205, 0
	v_mov_b32_e32 v206, 0
.Lbias_step:
	global_load_dwordx4 v[170:173], v[132:133], off offset:16
	ds_read_b128 v[156:159], v129 offset:0
	ds_read_b128 v[160:163], v129 offset:16
	ds_read_b128 v[182:185], v129 offset:4160
	ds_read_b128 v[186:189], v129 offset:4176
	ds_read_b128 v[226:229], v129 offset:8320
	ds_read_b128 v[230:233], v129 offset:8336
	ds_read_b128 v[234:237], v129 offset:12480
	ds_read_b128 v[238:241], v129 offset:12496
	s_waitcnt vmcnt(1)
	v_lshlrev_b32_e32 v148, 16, v134
	v_and_b32_e32 v149, 0xffff0000, v134
	v_lshlrev_b32_e32 v150, 16, v135
	v_and_b32_e32 v151, 0xffff0000, v135
	v_lshlrev_b32_e32 v152, 16, v136
	v_and_b32_e32 v153, 0xffff0000, v136
	v_lshlrev_b32_e32 v154, 16, v137
	v_and_b32_e32 v155, 0xffff0000, v137
	s_waitcnt lgkmcnt(4)
	v_fmac_f32_e32 v190, v148, v156
	v_fmac_f32_e32 v191, v148, v182
	v_fmac_f32_e32 v190, v149, v157
	v_fmac_f32_e32 v191, v149, v183
	v_fmac_f32_e32 v190, v150, v158
	v_fmac_f32_e32 v191, v150, v184
	v_fmac_f32_e32 v190, v151, v159
	v_fmac_f32_e32 v191, v151, v185
	v_fmac_f32_e32 v190, v152, v160
	v_fmac_f32_e32 v191, v152, v186
	v_fmac_f32_e32 v190, v153, v161
	v_fmac_f32_e32 v191, v153, v187
	v_fmac_f32_e32 v190, v154, v162
	v_fmac_f32_e32 v191, v154, v188
	v_fmac_f32_e32 v190, v155, v163
	v_fmac_f32_e32 v191, v155, v189
	ds_read_b128 v[156:159], v129 offset:16640
	ds_read_b128 v[160:163], v129 offset:16656
	ds_read_b128 v[182:185], v129 offset:20800
	ds_read_b128 v[186:189], v129 offset:20816
	s_waitcnt lgkmcnt(4)
	v_fmac_f32_e32 v192, v148, v226
	v_fmac_f32_e32 v193, v148, v234
	v_fmac_f32_e32 v192, v149, v227
	v_fmac_f32_e32 v193, v149, v235
	v_fmac_f32_e32 v192, v150, v228
	v_fmac_f32_e32 v193, v150, v236
	v_fmac_f32_e32 v192, v151, v229
	v_fmac_f32_e32 v193, v151, v237
	v_fmac_f32_e32 v192, v152, v230
	v_fmac_f32_e32 v193, v152, v238
	v_fmac_f32_e32 v192, v153, v231
	v_fmac_f32_e32 v193, v153, v239
	v_fmac_f32_e32 v192, v154, v232
	v_fmac_f32_e32 v193, v154, v240
	v_fmac_f32_e32 v192, v155, v233
	v_fmac_f32_e32 v193, v155, v241
	ds_read_b128 v[226:229], v129 offset:24960
	ds_read_b128 v[230:233], v129 offset:24976
	ds_read_b128 v[234:237], v129 offset:29120
	ds_read_b128 v[238:241], v129 offset:29136
	s_waitcnt lgkmcnt(4)
	v_fmac_f32_e32 v194, v148, v156
	v_fmac_f32_e32 v195, v148, v182
	v_fmac_f32_e32 v194, v149, v157
	v_fmac_f32_e32 v195, v149, v183
	v_fmac_f32_e32 v194, v150, v158
	v_fmac_f32_e32 v195, v150, v184
	v_fmac_f32_e32 v194, v151, v159
	v_fmac_f32_e32 v195, v151, v185
	v_fmac_f32_e32 v194, v152, v160
	v_fmac_f32_e32 v195, v152, v186
	v_fmac_f32_e32 v194, v153, v161
	v_fmac_f32_e32 v195, v153, v187
	v_fmac_f32_e32 v194, v154, v162
	v_fmac_f32_e32 v195, v154, v188
	v_fmac_f32_e32 v194, v155, v163
	v_fmac_f32_e32 v195, v155, v189
	ds_read_b128 v[156:159], v130 offset:0
	ds_read_b128 v[160:163], v130 offset:16
	ds_read_b128 v[182:185], v130 offset:4160
	ds_read_b128 v[186:189], v130 offset:4176
	s_waitcnt lgkmcnt(4)
	v_fmac_f32_e32 v196, v148, v226
	v_fmac_f32_e32 v197, v148, v234
	v_fmac_f32_e32 v196, v149, v227
	v_fmac_f32_e32 v197, v149, v235
	v_fmac_f32_e32 v196, v150, v228
	v_fmac_f32_e32 v197, v150, v236
	v_fmac_f32_e32 v196, v151, v229
	v_fmac_f32_e32 v197, v151, v237
	v_fmac_f32_e32 v196, v152, v230
	v_fmac_f32_e32 v197, v152, v238
	v_fmac_f32_e32 v196, v153, v231
	v_fmac_f32_e32 v197, v153, v239
	v_fmac_f32_e32 v196, v154, v232
	v_fmac_f32_e32 v197, v154, v240
	v_fmac_f32_e32 v196, v155, v233
	v_fmac_f32_e32 v197, v155, v241
	ds_read_b128 v[226:229], v130 offset:8320
	ds_read_b128 v[230:233], v130 offset:8336
	ds_read_b128 v[234:237], v130 offset:12480
	ds_read_b128 v[238:241], v130 offset:12496
	s_waitcnt lgkmcnt(4)
	v_fmac_f32_e32 v198, v148, v156
	v_fmac_f32_e32 v199, v148, v182
	v_fmac_f32_e32 v198, v149, v157
	v_fmac_f32_e32 v199, v149, v183
	v_fmac_f32_e32 v198, v150, v158
	v_fmac_f32_e32 v199, v150, v184
	v_fmac_f32_e32 v198, v151, v159
	v_fmac_f32_e32 v199, v151, v185
	v_fmac_f32_e32 v198, v152, v160
	v_fmac_f32_e32 v199, v152, v186
	v_fmac_f32_e32 v198, v153, v161
	v_fmac_f32_e32 v199, v153, v187
	v_fmac_f32_e32 v198, v154, v162
	v_fmac_f32_e32 v199, v154, v188
	v_fmac_f32_e32 v198, v155, v163
	v_fmac_f32_e32 v199, v155, v189
	ds_read_b128 v[156:159], v130 offset:16640
	ds_read_b128 v[160:163], v130 offset:16656
	ds_read_b128 v[182:185], v130 offset:20800
	ds_read_b128 v[186:189], v130 offset:20816
	s_waitcnt lgkmcnt(4)
	v_fmac_f32_e32 v200, v148, v226
	v_fmac_f32_e32 v201, v148, v234
	v_fmac_f32_e32 v200, v149, v227
	v_fmac_f32_e32 v201, v149, v235
	v_fmac_f32_e32 v200, v150, v228
	v_fmac_f32_e32 v201, v150, v236
	v_fmac_f32_e32 v200, v151, v229
	v_fmac_f32_e32 v201, v151, v237
	v_fmac_f32_e32 v200, v152, v230
	v_fmac_f32_e32 v201, v152, v238
	v_fmac_f32_e32 v200, v153, v231
	v_fmac_f32_e32 v201, v153, v239
	v_fmac_f32_e32 v200, v154, v232
	v_fmac_f32_e32 v201, v154, v240
	v_fmac_f32_e32 v200, v155, v233
	v_fmac_f32_e32 v201, v155, v241
	ds_read_b128 v[226:229], v130 offset:24960
	ds_read_b128 v[230:233], v130 offset:24976
	ds_read_b128 v[234:237], v130 offset:29120
	ds_read_b128 v[238:241], v130 offset:29136
	s_waitcnt lgkmcnt(4)
	v_fmac_f32_e32 v202, v148, v156
	v_fmac_f32_e32 v203, v148, v182
	v_fmac_f32_e32 v202, v149, v157
	v_fmac_f32_e32 v203, v149, v183
	v_fmac_f32_e32 v202, v150, v158
	v_fmac_f32_e32 v203, v150, v184
	v_fmac_f32_e32 v202, v151, v159
	v_fmac_f32_e32 v203, v151, v185
	v_fmac_f32_e32 v202, v152, v160
	v_fmac_f32_e32 v203, v152, v186
	v_fmac_f32_e32 v202, v153, v161
	v_fmac_f32_e32 v203, v153, v187
	v_fmac_f32_e32 v202, v154, v162
	v_fmac_f32_e32 v203, v154, v188
	v_fmac_f32_e32 v202, v155, v163
	v_fmac_f32_e32 v203, v155, v189
	ds_read_b128 v[156:159], v130 offset:33280
	ds_read_b128 v[160:163], v130 offset:33296
	s_waitcnt lgkmcnt(2)
	v_fmac_f32_e32 v204, v148, v226
	v_fmac_f32_e32 v205, v148, v234
	v_fmac_f32_e32 v204, v149, v227
	v_fmac_f32_e32 v205, v149, v235
	v_fmac_f32_e32 v204, v150, v228
	v_fmac_f32_e32 v205, v150, v236
	v_fmac_f32_e32 v204, v151, v229
	v_fmac_f32_e32 v205, v151, v237
	v_fmac_f32_e32 v204, v152, v230
	v_fmac_f32_e32 v205, v152, v238
	v_fmac_f32_e32 v204, v153, v231
	v_fmac_f32_e32 v205, v153, v239
	v_fmac_f32_e32 v204, v154, v232
	v_fmac_f32_e32 v205, v154, v240
	v_fmac_f32_e32 v204, v155, v233
	v_fmac_f32_e32 v205, v155, v241
	s_waitcnt lgkmcnt(0)
	v_fmac_f32_e32 v206, v148, v156
	v_fmac_f32_e32 v206, v149, v157
	v_fmac_f32_e32 v206, v150, v158
	v_fmac_f32_e32 v206, v151, v159
	v_fmac_f32_e32 v206, v152, v160
	v_fmac_f32_e32 v206, v153, v161
	v_fmac_f32_e32 v206, v154, v162
	v_fmac_f32_e32 v206, v155, v163
	s_waitcnt vmcnt(0)
	v_mov_b32_e32 v134, v170
	v_mov_b32_e32 v135, v171
	v_mov_b32_e32 v136, v172
	v_mov_b32_e32 v137, v173
	v_add_u32_e32 v129, 32, v129
	v_add_u32_e32 v130, 32, v130
	v_lshl_add_u64 v[132:133], v[132:133], 0, s[70:71]
	s_add_i32 s63, s63, 1
	s_cmp_lt_u32 s63, 32
	s_cbranch_scc1 .Lbias_step
	v_mov_b32_e32 v209, v190
	s_nop 1
	v_permlane16_swap_b32_e32 v190, v209
	v_add_f32_e32 v190, v190, v209
	v_mov_b32_e32 v209, v190
	s_nop 1
	v_permlane32_swap_b32_e32 v190, v209
	v_add_f32_e32 v190, v190, v209
	v_mov_b32_e32 v209, v191
	s_nop 1
	v_permlane16_swap_b32_e32 v191, v209
	v_add_f32_e32 v191, v191, v209
	v_mov_b32_e32 v209, v191
	s_nop 1
	v_permlane32_swap_b32_e32 v191, v209
	v_add_f32_e32 v191, v191, v209
	v_mov_b32_e32 v209, v192
	s_nop 1
	v_permlane16_swap_b32_e32 v192, v209
	v_add_f32_e32 v192, v192, v209
	v_mov_b32_e32 v209, v192
	s_nop 1
	v_permlane32_swap_b32_e32 v192, v209
	v_add_f32_e32 v192, v192, v209
	v_mov_b32_e32 v209, v193
	s_nop 1
	v_permlane16_swap_b32_e32 v193, v209
	v_add_f32_e32 v193, v193, v209
	v_mov_b32_e32 v209, v193
	s_nop 1
	v_permlane32_swap_b32_e32 v193, v209
	v_add_f32_e32 v193, v193, v209
	v_mov_b32_e32 v209, v194
	s_nop 1
	v_permlane16_swap_b32_e32 v194, v209
	v_add_f32_e32 v194, v194, v209
	v_mov_b32_e32 v209, v194
	s_nop 1
	v_permlane32_swap_b32_e32 v194, v209
	v_add_f32_e32 v194, v194, v209
	v_mov_b32_e32 v209, v195
	s_nop 1
	v_permlane16_swap_b32_e32 v195, v209
	v_add_f32_e32 v195, v195, v209
	v_mov_b32_e32 v209, v195
	s_nop 1
	v_permlane32_swap_b32_e32 v195, v209
	v_add_f32_e32 v195, v195, v209
	v_mov_b32_e32 v209, v196
	s_nop 1
	v_permlane16_swap_b32_e32 v196, v209
	v_add_f32_e32 v196, v196, v209
	v_mov_b32_e32 v209, v196
	s_nop 1
	v_permlane32_swap_b32_e32 v196, v209
	v_add_f32_e32 v196, v196, v209
	v_mov_b32_e32 v209, v197
	s_nop 1
	v_permlane16_swap_b32_e32 v197, v209
	v_add_f32_e32 v197, v197, v209
	v_mov_b32_e32 v209, v197
	s_nop 1
	v_permlane32_swap_b32_e32 v197, v209
	v_add_f32_e32 v197, v197, v209
	v_mov_b32_e32 v209, v198
	s_nop 1
	v_permlane16_swap_b32_e32 v198, v209
	v_add_f32_e32 v198, v198, v209
	v_mov_b32_e32 v209, v198
	s_nop 1
	v_permlane32_swap_b32_e32 v198, v209
	v_add_f32_e32 v198, v198, v209
	v_mov_b32_e32 v209, v199
	s_nop 1
	v_permlane16_swap_b32_e32 v199, v209
	v_add_f32_e32 v199, v199, v209
	v_mov_b32_e32 v209, v199
	s_nop 1
	v_permlane32_swap_b32_e32 v199, v209
	v_add_f32_e32 v199, v199, v209
	v_mov_b32_e32 v209, v200
	s_nop 1
	v_permlane16_swap_b32_e32 v200, v209
	v_add_f32_e32 v200, v200, v209
	v_mov_b32_e32 v209, v200
	s_nop 1
	v_permlane32_swap_b32_e32 v200, v209
	v_add_f32_e32 v200, v200, v209
	v_mov_b32_e32 v209, v201
	s_nop 1
	v_permlane16_swap_b32_e32 v201, v209
	v_add_f32_e32 v201, v201, v209
	v_mov_b32_e32 v209, v201
	s_nop 1
	v_permlane32_swap_b32_e32 v201, v209
	v_add_f32_e32 v201, v201, v209
	v_mov_b32_e32 v209, v202
	s_nop 1
	v_permlane16_swap_b32_e32 v202, v209
	v_add_f32_e32 v202, v202, v209
	v_mov_b32_e32 v209, v202
	s_nop 1
	v_permlane32_swap_b32_e32 v202, v209
	v_add_f32_e32 v202, v202, v209
	v_mov_b32_e32 v209, v203
	s_nop 1
	v_permlane16_swap_b32_e32 v203, v209
	v_add_f32_e32 v203, v203, v209
	v_mov_b32_e32 v209, v203
	s_nop 1
	v_permlane32_swap_b32_e32 v203, v209
	v_add_f32_e32 v203, v203, v209
	v_mov_b32_e32 v209, v204
	s_nop 1
	v_permlane16_swap_b32_e32 v204, v209
	v_add_f32_e32 v204, v204, v209
	v_mov_b32_e32 v209, v204
	s_nop 1
	v_permlane32_swap_b32_e32 v204, v209
	v_add_f32_e32 v204, v204, v209
	v_mov_b32_e32 v209, v205
	s_nop 1
	v_permlane16_swap_b32_e32 v205, v209
	v_add_f32_e32 v205, v205, v209
	v_mov_b32_e32 v209, v205
	s_nop 1
	v_permlane32_swap_b32_e32 v205, v209
	v_add_f32_e32 v205, v205, v209
	v_mov_b32_e32 v209, v206
	s_nop 1
	v_permlane16_swap_b32_e32 v206, v209
	v_add_f32_e32 v206, v206, v209
	v_mov_b32_e32 v209, v206
	s_nop 1
	v_permlane32_swap_b32_e32 v206, v209
	v_add_f32_e32 v206, v206, v209
	v_cmp_gt_u32_e32 vcc, 16, v0
	s_and_saveexec_b64 s[66:67], vcc
	global_store_dword v128, v190, s[46:47]
	v_add_u32_e32 v128, s64, v128
	global_store_dword v128, v191, s[46:47]
	v_add_u32_e32 v128, s64, v128
	global_store_dword v128, v192, s[46:47]
	v_add_u32_e32 v128, s64, v128
	global_store_dword v128, v193, s[46:47]
	v_add_u32_e32 v128, s64, v128
	global_store_dword v128, v194, s[46:47]
	v_add_u32_e32 v128, s64, v128
	global_store_dword v128, v195, s[46:47]
	v_add_u32_e32 v128, s64, v128
	global_store_dword v128, v196, s[46:47]
	v_add_u32_e32 v128, s64, v128
	global_store_dword v128, v197, s[46:47]
	v_add_u32_e32 v128, s64, v128
	global_store_dword v128, v198, s[46:47]
	v_add_u32_e32 v128, s64, v128
	global_store_dword v128, v199, s[46:47]
	v_add_u32_e32 v128, s64, v128
	global_store_dword v128, v200, s[46:47]
	v_add_u32_e32 v128, s64, v128
	global_store_dword v128, v201, s[46:47]
	v_add_u32_e32 v128, s64, v128
	global_store_dword v128, v202, s[46:47]
	v_add_u32_e32 v128, s64, v128
	global_store_dword v128, v203, s[46:47]
	v_add_u32_e32 v128, s64, v128
	global_store_dword v128, v204, s[46:47]
	v_add_u32_e32 v128, s64, v128
	global_store_dword v128, v205, s[46:47]
	v_add_u32_e32 v128, s64, v128
	global_store_dword v128, v206, s[46:47]
	s_or_b64 exec, exec, s[66:67]
	s_branch .LBB0_162
